# v5 + one static s_setprio 1 for waves 4-7 during the attention phase (strategy 7.4), reset to 0 at phase end
# baseline (speedup 1.0000x reference)
; __device__ __forceinline__ int v_st(int k, int c) { const int kk = (k & ~0xC) | ((k & 4) << 1) | ((k & 8) >> 1); return ((kk >> 3) * 4 + (c >> 5)) * 512 + ((kk & 7) * 32 + (c & 31)) * 2; }
; #define VMW() asm volatile("s_waitcnt vmcnt(0)" ::: "memory")
; #define SLOAD(Kp, Vp, k0) do { S.st_v0 = load8((Vp) + (size_t)((k0) + sr) * C::VS + sc); S.st_v1 = load8((Vp) + (size_t)((k0) + 32 + sr) * C::VS + sc); \
;         const bf16_t* kp_ = (Kp) + (size_t)((k0) + (tid >> 3)) * C::KS + (tid & 7) * 8; \
;         _Pragma("unroll") for (int i_ = 0; i_ < C::KST; ++i_) S.st_k[i_] = load8(kp_ + 64 * i_); } while (0)
; #define SWRITE_K(bf) do { char* kw_ = K_lds + (bf) * C::SHM_K + (tid >> 3) * C::RB + (tid & 7) * 16; \
;         _Pragma("unroll") for (int i_ = 0; i_ < C::KST; ++i_) *(bf16x8*)(kw_ + 128 * i_) = S.st_k[i_]; } while (0)
; #define SWRITE_V(bf) do { *(bf16x8*)(V_lds + (bf) * SHM_V + vst0) = S.st_v0; *(bf16x8*)(V_lds + (bf) * SHM_V + vst1) = S.st_v1; } while (0)
; template <class C>
; __device__ __forceinline__ void prime(const BlockRef& cur, char* lds, Seam<C>& S) {
;     int tid_ = threadIdx.x; asm volatile("" : "+v"(tid_));
;     const int tid = tid_, wid = __builtin_amdgcn_readfirstlane(tid >> 6), lane = tid & 63, r32 = lane & 31, hi = lane >> 5;
;     const int sr = tid >> 4, sc = (tid & 15) * 8, vst0 = v_st(sr, sc), vst1 = v_st(32 + sr, sc); char* V_lds = lds; char* K_lds = lds + 2 * SHM_V;
; #pragma unroll
;     for (int d0 = 0; d0 < C::NQ; ++d0) S.qr[d0] = load8(cur.Q + (size_t)(wid * QBLK + r32) * C::QS + d0 * 16 + hi * 8);
;     SLOAD(cur.K, cur.V, 0); VMW(); SWRITE_K(0); SWRITE_V(0);
;     SLOAD(cur.K, cur.V, KVBLK);
;     __syncthreads();
; }
; __device__ __forceinline__ void phase5(const Params& p, Frame& F, char* lds) {
;     unsigned char* ws = p.ws;
;     {
;         att::Seam<CfgMLA> S;
;         const int total = 512; int L = F.vcu, pass = 0;
;         if (L < total) {
;             att::BlockRef cur = mla_ref(ws, L, 0);
;             att::prime<CfgMLA>(cur, lds, S);
.LBB0_456:
	s_cmp_lt_i32 s2, 6
	s_cselect_b64 s[0:1], -1, 0
	s_cmp_gt_i32 s3, 5
	s_cselect_b64 s[2:3], -1, 0
	s_and_b64 s[0:1], s[0:1], s[2:3]
	v_writelane_b32 v240, s0, 12
	s_andn2_b64 vcc, exec, s[0:1]
	s_nop 0
	v_writelane_b32 v240, s1, 13
	s_cbranch_vccnz .LBB0_771
	v_readlane_b32 s0, v240, 2
	s_cmpk_gt_i32 s0, 0x1ff
	s_cbranch_scc1 .LBB0_771
	v_readfirstlane_b32 s0, v222
	s_lshr_b32 s0, s0, 6
	s_cmp_ge_u32 s0, 4
	s_cbranch_scc0 .Lprio5_skip
	s_setprio 1
.Lprio5_skip:
	v_writelane_b32 v240, s88, 14
	s_load_dwordx2 s[8:9], s[78:79], 0xc0
	v_readlane_b32 s81, v240, 2
	s_ashr_i32 s10, s81, 7
	s_ashr_i32 s11, s10, 31
	s_bfe_u32 s1, s81, 0x30004
	s_lshl_b64 s[2:3], s[10:11], 13
	s_waitcnt lgkmcnt(0)
	s_add_u32 s6, s8, 0x1f000000
	s_addc_u32 s7, s9, 0
	s_lshl_b32 s0, s81, 8
	s_and_b32 s0, s0, 0xf00
	s_or_b32 s2, s2, s0
	s_mul_i32 s4, s3, 0xc00
	s_mul_hi_u32 s5, s2, 0xc00
	s_add_i32 s5, s5, s4
	s_mul_i32 s4, s2, 0xc00
	s_add_u32 s4, s6, s4
	v_writelane_b32 v240, s6, 15
	s_addc_u32 s5, s7, s5
	s_mul_i32 s6, s1, 0x180
	s_add_u32 s82, s4, s6
	s_addc_u32 s83, s5, 0
	v_writelane_b32 v240, s7, 17
	s_add_u32 s7, s8, 0x2d000000
	s_addc_u32 s13, s9, 0
	s_mul_i32 s5, s10, 0x1800000
	s_mul_hi_i32 s4, s10, 0x1800000
	s_add_u32 s5, s7, s5
	v_writelane_b32 v240, s7, 19
	s_addc_u32 s4, s13, s4
	v_writelane_b32 v240, s13, 20
	s_add_u32 s74, s5, s6
	s_addc_u32 s75, s4, 0
	v_writelane_b32 v240, s10, 21
	s_lshl_b64 s[4:5], s[10:11], 25
	s_add_u32 s6, s8, s4
	v_writelane_b32 v240, s11, 22
	s_addc_u32 s5, s9, s5
	s_lshl_b32 s4, s1, 8
	s_lshl_b32 s1, s1, 9
	v_writelane_b32 v240, s6, 23
	s_add_u32 s1, s6, s1
	v_writelane_b32 v240, s5, 24
	s_addc_u32 s5, s5, 0
	s_add_u32 s96, s1, 0x25000100
	s_addc_u32 s97, s5, 0
	s_lshl_b64 s[2:3], s[2:3], 12
	s_add_u32 s1, s8, s2
	s_addc_u32 s2, s9, s3
	s_add_u32 s1, s1, s4
	s_addc_u32 s2, s2, 0
	v_mov_b32_e32 v2, v222
	s_add_u32 s36, s1, 0x33000400
	s_addc_u32 s37, s2, 0
	v_readfirstlane_b32 s1, v2
	s_ashr_i32 s1, s1, 1
	s_movk_i32 s2, 0xffe0
	v_mov_b32_e32 v0, s1
	s_movk_i32 s12, 0xc00
	v_bfi_b32 v4, s2, v0, v2
	v_mov_b64_e32 v[0:1], s[82:83]
	v_ashrrev_i32_e32 v20, 4, v2
	v_mad_i64_i32 v[0:1], s[2:3], v4, s12, v[0:1]
	v_lshrrev_b32_e32 v4, 1, v2
	v_lshlrev_b32_e32 v34, 3, v2
	v_and_b32_e32 v180, 16, v4
	v_mov_b32_e32 v181, 0
	v_ashrrev_i32_e32 v21, 31, v20
	v_and_b32_e32 v3, 0x78, v34
	v_add_u32_e32 v22, 32, v20
	v_lshl_add_u64 v[24:25], v[0:1], 0, v[180:181]
	v_lshlrev_b64 v[0:1], 12, v[20:21]
	v_lshl_add_u64 v[0:1], s[96:97], 0, v[0:1]
	v_lshlrev_b32_e32 v180, 1, v3
	v_ashrrev_i32_e32 v23, 31, v22
	v_lshl_add_u64 v[26:27], v[0:1], 0, v[180:181]
	v_lshlrev_b64 v[0:1], 12, v[22:23]
	v_lshlrev_b32_e32 v35, 4, v2
	v_lshl_add_u64 v[0:1], s[96:97], 0, v[0:1]
	v_ashrrev_i32_e32 v21, 3, v2
	v_mov_b64_e32 v[30:31], s[74:75]
	v_lshl_add_u64 v[28:29], v[0:1], 0, v[180:181]
	v_mad_i64_i32 v[0:1], s[2:3], v21, s12, v[30:31]
	v_and_b32_e32 v180, 0x70, v35
	v_lshl_add_u64 v[32:33], v[0:1], 0, v[180:181]
	s_mov_b32 s1, 0x40000
	global_load_dwordx4 v[96:99], v[24:25], off
	global_load_dwordx4 v[100:103], v[24:25], off offset:32
	global_load_dwordx4 v[104:107], v[24:25], off offset:64
	global_load_dwordx4 v[108:111], v[24:25], off offset:96
	global_load_dwordx4 v[112:115], v[24:25], off offset:128
	global_load_dwordx4 v[116:119], v[24:25], off offset:160
	global_load_dwordx4 v[120:123], v[24:25], off offset:192
	global_load_dwordx4 v[124:127], v[24:25], off offset:224
	global_load_dwordx4 v[0:3], v[32:33], off
	global_load_dwordx4 v[4:7], v[32:33], off offset:128
	global_load_dwordx4 v[8:11], v[32:33], off offset:256
	global_load_dwordx4 v[128:131], v[24:25], off offset:256
	global_load_dwordx4 v[136:139], v[24:25], off offset:288
	global_load_dwordx4 v[132:135], v[24:25], off offset:320
	global_load_dwordx4 v[140:143], v[24:25], off offset:352
	global_load_dwordx4 v[12:15], v[26:27], off
	global_load_dwordx4 v[16:19], v[28:29], off
	v_add_co_u32_e32 v24, vcc, s1, v26
	s_mov_b32 s1, 0x60000
	s_nop 0
	v_addc_co_u32_e32 v25, vcc, 0, v27, vcc
	s_waitcnt vmcnt(0)
	v_add_co_u32_e32 v26, vcc, s1, v26
	v_add_u32_e32 v23, 64, v21
	s_nop 0
	v_addc_co_u32_e32 v27, vcc, 0, v27, vcc
	global_load_dwordx4 v[144:147], v[24:25], off
	global_load_dwordx4 v[148:151], v[26:27], off
	v_mad_i64_i32 v[24:25], s[2:3], v23, s12, v[30:31]
	v_lshl_add_u64 v[24:25], v[24:25], 0, v[180:181]
	global_load_dwordx4 v[152:155], v[24:25], off
	global_load_dwordx4 v[156:159], v[24:25], off offset:128
	global_load_dwordx4 v[160:163], v[24:25], off offset:256
	v_and_b32_e32 v23, 0xfffff0, v20
	v_lshlrev_b32_e32 v24, 1, v20
	v_and_or_b32 v23, v24, 8, v23
	v_lshrrev_b32_e32 v24, 1, v20
	v_and_b32_e32 v20, 3, v20
	v_and_or_b32 v20, v24, 4, v20
	v_and_b32_e32 v24, 0xfffff0, v22
	v_lshlrev_b32_e32 v22, 1, v22
	s_movk_i32 s1, 0x190
	v_lshrrev_b32_e32 v23, 1, v23
	v_bfe_u32 v25, v34, 5, 2
	v_and_or_b32 v22, v22, 8, v24
	v_mul_lo_u32 v21, v21, s1
	v_or_b32_e32 v23, v23, v25
	v_lshrrev_b32_e32 v22, 1, v22
	v_add3_u32 v21, 0, v21, v180
	v_or_b32_e32 v22, v22, v25
	v_and_b32_e32 v24, 48, v35
	s_waitcnt vmcnt(0)
	ds_write_b128 v21, v[0:3] offset:32768
	ds_write_b128 v21, v[4:7] offset:32896
	ds_write_b128 v21, v[8:11] offset:33024
	v_lshlrev_b32_e32 v0, 9, v23
	v_lshl_add_u32 v1, v20, 6, 0
	v_lshlrev_b32_e32 v22, 9, v22
	v_add3_u32 v0, v1, v0, v24
	ds_write_b128 v0, v[12:15]
	v_add3_u32 v0, v1, v22, v24
	ds_write_b128 v0, v[16:19]
	s_add_u32 s72, s8, 0x6300000
	v_writelane_b32 v240, s8, 25
	v_mbcnt_lo_u32_b32 v0, -1, 0
	s_mov_b32 s85, 0
	v_writelane_b32 v240, s9, 26
	s_addc_u32 s73, s9, 0
	v_mov_b32_e32 v192, 0x358637bd
	s_mov_b32 s33, 0x41000000
	v_mbcnt_hi_u32_b32 v193, -1, v0
	v_mov_b32_e32 v194, 0xff800000
	s_mov_b32 s76, 0
	s_mov_b32 s2, s0
	s_mov_b64 s[92:93], s[36:37]
	s_mov_b64 s[90:91], s[96:97]
	s_mov_b64 s[88:89], s[74:75]
	s_waitcnt lgkmcnt(0)
	s_barrier
	v_writelane_b32 v240, s86, 27
	s_branch .LBB0_460

; __device__ __forceinline__ void phase5(const Params& p, Frame& F, char* lds) {
;     ...
;         if (L < total) {
;             att::BlockRef cur = mla_ref(ws, L, 0);
;             att::prime<CfgMLA>(cur, lds, S);
;             for (;;) {
;                 int Ln = L, passn = pass + 1; bool last = false;
;                 if (pass == 1) { passn = 0; if (L + F.G < total) Ln = L + F.G; else last = true; }
;                 const att::BlockRef nxt = last ? cur : mla_ref(ws, Ln, passn);
;                 att::block<CfgMLA>(cur, nxt, SEQ, lds, S, p.in[I_GQMLA], (const float2*)(ws + WS_ROPE));
;                 if (last) break;
;                 cur = nxt; L = Ln; pass = passn;
;             }
;         }
;     }
;     {
;         att::Seam<CfgX> S;
;         const int total = 512; int L = F.vcu;
;         if (L < total) {
;             att::BlockRef cur = x_ref(ws, L);
;             att::prime<CfgX>(cur, lds, S);
;             for (;;) {
;                 const bool last = !(L + F.G < total); const int Ln = last ? L : L + F.G;
;                 const att::BlockRef nxt = last ? cur : x_ref(ws, Ln);
;                 att::block<CfgX>(cur, nxt, MEML, lds, S, p.in[I_GQX], nullptr);
;                 if (last) break;
;                 cur = nxt; L = Ln;
;             }
;         }
;     }
; }
.LBB0_770:
	v_readlane_b32 s88, v240, 14
	v_readlane_b32 s86, v240, 27
	s_setprio 0
